# natten: second query group's P.V chain reads its 5 remaining V^T fragments in one batch (v228-v247) instead of one LDS round trip per MFMA
# speedup vs baseline: 1.0011x; 1.0006x over previous
.LBB0_512:
	s_add_i32 s36, s46, s63
	s_add_i32 s36, s36, -4
	v_cmp_ge_u32_e32 vcc, s36, v135
	v_cmp_le_u32_e64 s[36:37], s36, v180
	s_and_b64 s[82:83], vcc, s[36:37]
	s_and_saveexec_b64 s[36:37], s[82:83]
	s_cbranch_execz .LBB0_514
	s_and_b32 s81, s80, 0x8000
	s_add_i32 s81, s81, 0
	v_add_u32_e32 v181, s81, v153
	ds_read_b128 v[184:187], v181
	v_add_u32_e32 v181, s81, v154
	ds_read_b128 v[188:191], v181
	v_add_u32_e32 v181, s81, v155
	ds_read_b128 v[192:195], v181
	v_add_u32_e32 v181, s81, v157
	ds_read_b128 v[196:199], v181
	v_add_u32_e32 v181, s81, v156
	ds_read_b128 v[200:203], v181
	s_waitcnt lgkmcnt(4)
	v_mfma_f32_16x16x32_bf16 v[184:187], v[184:187], v[18:21], 0
	v_add_u32_e32 v182, s81, v159
	v_add_u32_e32 v208, s81, v169
	v_add_u32_e32 v210, v116, v176
	s_waitcnt lgkmcnt(2)
	v_mfma_f32_16x16x32_bf16 v[184:187], v[192:195], v[22:25], v[184:187]
	v_add3_u32 v219, s81, v161, v151
	v_add_u32_e32 v214, s81, v171
	v_add_u32_e32 v220, 0x10270, v210
	s_waitcnt lgkmcnt(1)
	v_mfma_f32_16x16x32_bf16 v[184:187], v[196:199], v[26:29], v[184:187]
	ds_read_b128 v[196:199], v182
	v_add_u32_e32 v181, s81, v158
	ds_read_b128 v[192:195], v181
	v_mfma_f32_16x16x32_bf16 v[188:191], v[188:191], v[18:21], 0
	v_add_u32_e32 v181, s81, v160
	ds_read_b128 v[204:207], v181
	v_add_u32_e32 v181, v116, v178
	s_waitcnt lgkmcnt(3)
	v_mfma_f32_16x16x32_bf16 v[188:191], v[200:203], v[22:25], v[188:191]
	v_add_u32_e32 v182, 0x102b0, v181
	v_add_u32_e32 v200, s81, v167
	v_add_u32_e32 v222, 0x10278, v210
	s_waitcnt lgkmcnt(1)
	v_mfma_f32_16x16x32_bf16 v[188:191], v[192:195], v[26:29], v[188:191]
	v_add_u32_e32 v224, 0x10280, v210
	v_add_u32_e32 v226, 0x10288, v210
	v_mfma_f32_16x16x32_bf16 v[184:187], v[196:199], v[30:33], v[184:187]
	v_add_u32_e32 v196, 0x102b8, v181
	v_add_u32_e32 v197, 0x102c0, v181
	v_add_u32_e32 v181, 0x102c8, v181
	ds_read2_b32 v[192:193], v182 offset1:1
	ds_read2_b32 v[194:195], v196 offset1:1
	ds_read2_b32 v[196:197], v197 offset1:1
	ds_read2_b32 v[198:199], v181 offset1:1
	s_waitcnt lgkmcnt(4)
	v_mfma_f32_16x16x32_bf16 v[188:191], v[204:207], v[30:33], v[188:191]
	s_waitcnt lgkmcnt(3)
	v_add_f32_e32 v181, v184, v192
	v_add_f32_e32 v184, v185, v193
	v_mul_f32_e32 v184, 0x3fb8aa3b, v184
	v_exp_f32_e32 v209, v184
	v_add_u32_e32 v192, s81, v165
	s_waitcnt lgkmcnt(1)
	s_nop 0
	v_add_f32_e32 v184, v197, v189
	v_mul_f32_e32 v184, 0x3fb8aa3b, v184
	v_exp_f32_e32 v211, v184
	v_add_f32_e32 v184, v186, v194
	v_mul_f32_e32 v184, 0x3fb8aa3b, v184
	v_exp_f32_e32 v212, v184
	s_waitcnt lgkmcnt(0)
	v_add_f32_e32 v184, v198, v190
	v_mul_f32_e32 v184, 0x3fb8aa3b, v184
	v_exp_f32_e32 v213, v184
	v_add_f32_e32 v184, v187, v195
	v_mul_f32_e32 v184, 0x3fb8aa3b, v184
	v_exp_f32_e32 v215, v184
	v_add_f32_e32 v184, v199, v191
	v_mul_f32_e32 v184, 0x3fb8aa3b, v184
	v_exp_f32_e32 v217, v184
	v_add_u32_e32 v184, s81, v164
	ds_read_b128 v[184:187], v184
	v_add_f32_e32 v182, v196, v188
	v_add_u32_e32 v188, s81, v166
	ds_read_b128 v[188:191], v188
	v_add_u32_e32 v196, s81, v168
	s_waitcnt lgkmcnt(1)
	v_mfma_f32_16x16x32_bf16 v[184:187], v[184:187], v[54:57], 0
	ds_read_b128 v[192:195], v192
	ds_read_b128 v[196:199], v196
	v_add_u32_e32 v204, s81, v170
	ds_read_b128 v[200:203], v200
	ds_read_b128 v[204:207], v204
	s_waitcnt lgkmcnt(4)
	v_mfma_f32_16x16x32_bf16 v[184:187], v[188:191], v[62:65], v[184:187]
	ds_read_b128 v[188:191], v208
	v_mul_f32_e32 v181, 0x3fb8aa3b, v181
	v_mul_f32_e32 v182, 0x3fb8aa3b, v182
	s_waitcnt lgkmcnt(4)
	v_mfma_f32_16x16x32_bf16 v[192:195], v[192:195], v[54:57], 0
	v_exp_f32_e32 v181, v181
	v_exp_f32_e32 v182, v182
	v_cndmask_b32_e64 v212, v212, 0, s[96:97]
	s_waitcnt lgkmcnt(2)
	v_mfma_f32_16x16x32_bf16 v[192:195], v[200:203], v[62:65], v[192:195]
	v_cndmask_b32_e64 v216, v215, 0, s[94:95]
	v_cndmask_b32_e64 v210, v182, 0, s[88:89]
	v_cndmask_b32_e64 v218, v217, 0, s[16:17]
	v_mfma_f32_16x16x32_bf16 v[184:187], v[196:199], v[70:73], v[184:187]
	ds_read_b128 v[196:199], v214
	ds_read2_b32 v[220:221], v220 offset1:1
	ds_read2_b32 v[222:223], v222 offset1:1
	ds_read2_b32 v[224:225], v224 offset1:1
	ds_read2_b32 v[226:227], v226 offset1:1
	v_cndmask_b32_e64 v208, v181, 0, s[86:87]
	s_waitcnt lgkmcnt(5)
	v_mfma_f32_16x16x32_bf16 v[188:191], v[188:191], v[70:73], v[192:195]
	v_cndmask_b32_e64 v214, v213, 0, s[38:39]
	v_cvt_pk_bf16_f32 v201, v212, v216
	v_cvt_pk_bf16_f32 v203, v214, v218
	v_mfma_f32_16x16x32_bf16 v[184:187], v[204:207], v[78:81], v[184:187]
	v_cndmask_b32_e64 v204, v209, 0, s[90:91]
	ds_read_b128 v[192:195], v219 offset:16384
	v_cndmask_b32_e64 v206, v211, 0, s[92:93]
	v_cvt_pk_bf16_f32 v200, v208, v204
	v_cvt_pk_bf16_f32 v202, v210, v206
	s_waitcnt lgkmcnt(5)
	v_mfma_f32_16x16x32_bf16 v[188:191], v[196:199], v[78:81], v[188:191]
	s_waitcnt lgkmcnt(4)
	s_nop 1
	v_add_f32_e32 v181, v184, v220
	ds_read_b128 v[196:199], v219 offset:16640
	v_mul_f32_e32 v181, 0x3fb8aa3b, v181
	s_waitcnt lgkmcnt(1)
	v_mfma_f32_16x16x32_bf16 v[110:113], v[192:195], v[200:203], v[110:113]
	ds_read_b128 v[192:195], v219 offset:16896
	v_exp_f32_e32 v181, v181
	v_add_f32_e32 v182, v224, v188
	v_mul_f32_e32 v182, 0x3fb8aa3b, v182
	v_exp_f32_e32 v182, v182
	v_cndmask_b32_e64 v209, v181, 0, s[18:19]
	v_add_f32_e32 v181, v185, v221
	v_mul_f32_e32 v181, 0x3fb8aa3b, v181
	v_exp_f32_e32 v181, v181
	s_waitcnt lgkmcnt(1)
	v_mfma_f32_16x16x32_bf16 v[106:109], v[196:199], v[200:203], v[106:109]
	ds_read_b128 v[196:199], v219 offset:17152
	v_cndmask_b32_e64 v211, v182, 0, s[20:21]
	v_add_f32_e32 v182, v225, v189
	s_waitcnt lgkmcnt(1)
	v_mfma_f32_16x16x32_bf16 v[102:105], v[192:195], v[200:203], v[102:105]
	ds_read_b128 v[192:195], v219 offset:17408
	v_cndmask_b32_e64 v205, v181, 0, s[22:23]
	v_add_f32_e32 v181, v186, v222
	v_add_f32_e32 v184, v226, v190
	v_mul_f32_e32 v182, 0x3fb8aa3b, v182
	v_mul_f32_e32 v181, 0x3fb8aa3b, v181
	v_mul_f32_e32 v184, 0x3fb8aa3b, v184
	v_exp_f32_e32 v182, v182
	v_exp_f32_e32 v181, v181
	v_exp_f32_e32 v184, v184
	v_add3_u32 v220, s81, v172, v151
	s_waitcnt lgkmcnt(1)
	v_mfma_f32_16x16x32_bf16 v[98:101], v[196:199], v[200:203], v[98:101]
	ds_read_b128 v[196:199], v219 offset:17664
	v_cndmask_b32_e64 v207, v182, 0, s[24:25]
	v_cndmask_b32_e64 v213, v181, 0, s[26:27]
	v_cndmask_b32_e64 v215, v184, 0, s[28:29]
	s_waitcnt lgkmcnt(1)
	v_mfma_f32_16x16x32_bf16 v[94:97], v[192:195], v[200:203], v[94:97]
	ds_read_b128 v[192:195], v219 offset:17920
	v_add_f32_e32 v181, v187, v223
	ds_read_b128 v[184:187], v219 offset:18176
	v_add_f32_e32 v182, v227, v191
	ds_read_b128 v[188:191], v220 offset:16384
	v_mul_f32_e32 v181, 0x3fb8aa3b, v181
	v_mul_f32_e32 v182, 0x3fb8aa3b, v182
	v_exp_f32_e32 v181, v181
	v_exp_f32_e32 v182, v182
	s_waitcnt lgkmcnt(2)
	v_mfma_f32_16x16x32_bf16 v[86:89], v[192:195], v[200:203], v[86:89]
	v_cvt_pk_bf16_f32 v192, v209, v205
	v_cndmask_b32_e64 v217, v181, 0, s[30:31]
	v_cndmask_b32_e64 v219, v182, 0, s[34:35]
	s_waitcnt lgkmcnt(1)
	v_mfma_f32_16x16x32_bf16 v[82:85], v[184:187], v[200:203], v[82:85]
	ds_read_b128 v[184:187], v220 offset:16640
	v_cvt_pk_bf16_f32 v193, v213, v217
	v_cvt_pk_bf16_f32 v194, v211, v207
	v_cvt_pk_bf16_f32 v195, v215, v219
	v_mfma_f32_16x16x32_bf16 v[90:93], v[196:199], v[200:203], v[90:93]
	ds_read_b128 v[196:199], v220 offset:17920
	ds_read_b128 v[228:231], v220 offset:16896
	ds_read_b128 v[232:235], v220 offset:17152
	ds_read_b128 v[236:239], v220 offset:17408
	ds_read_b128 v[240:243], v220 offset:17664
	ds_read_b128 v[244:247], v220 offset:18176
	v_pk_add_f32 v[200:201], v[208:209], v[210:211]
	v_pk_add_f32 v[202:203], v[204:205], v[206:207]
	s_waitcnt lgkmcnt(7)
	v_mfma_f32_16x16x32_bf16 v[74:77], v[188:191], v[192:195], v[74:77]
	v_pk_add_f32 v[200:201], v[200:201], 0 op_sel_hi:[1,0]
	s_waitcnt lgkmcnt(6)
	v_mfma_f32_16x16x32_bf16 v[66:69], v[184:187], v[192:195], v[66:69]
	s_waitcnt lgkmcnt(4)
	v_mfma_f32_16x16x32_bf16 v[58:61], v[228:231], v[192:195], v[58:61]
	s_waitcnt lgkmcnt(3)
	v_mfma_f32_16x16x32_bf16 v[50:53], v[232:235], v[192:195], v[50:53]
	s_waitcnt lgkmcnt(2)
	v_mfma_f32_16x16x32_bf16 v[46:49], v[236:239], v[192:195], v[46:49]
	s_waitcnt lgkmcnt(1)
	v_mfma_f32_16x16x32_bf16 v[42:45], v[240:243], v[192:195], v[42:45]
	v_add_f32_e64 v184, v202, v200
	v_add_f32_e64 v185, v203, v201
	v_pk_add_f32 v[186:187], v[212:213], v[214:215]
	v_mfma_f32_16x16x32_bf16 v[38:41], v[196:199], v[192:195], v[38:41]
	v_add_f32_e64 v184, v186, v184
	v_add_f32_e64 v185, v187, v185
	v_pk_add_f32 v[186:187], v[216:217], v[218:219]
	s_waitcnt lgkmcnt(0)
	v_mfma_f32_16x16x32_bf16 v[34:37], v[244:247], v[192:195], v[34:37]
	v_add_f32_e64 v184, v186, v184
	v_add_f32_e64 v185, v187, v185
	v_pk_add_f32 v[144:145], v[144:145], v[184:185]
